# PEER stage B: workgroup barrier every second gather iteration instead of every iteration (looser lockstep, same L2 locality), on top of v121
# speedup vs baseline: 1.0100x; 1.0092x over previous
.LBB0_790:
	s_bitcmp1_b32 s16, 1
	s_cbranch_scc1 .Lpb_skip
	s_barrier
.Lpb_skip:
	s_not_b32 s17, s11
	s_mul_i32 s15, s81, s11
	s_mul_i32 s17, s81, s17
	s_add_i32 s17, s17, s16
	s_sub_i32 s15, s16, s15
	s_not_b32 s14, s9
	s_add_i32 s15, s15, 1
	s_add_i32 s83, s11, 1
	s_add_i32 s17, s17, 1
	s_cmp_ge_u32 s15, s81
	s_cselect_b32 s83, s83, s11
	s_cselect_b32 s15, s17, s15
	s_add_i32 s17, s83, 1
	s_cmp_ge_u32 s15, s81
	s_cselect_b32 s83, s17, s83
	s_mul_i32 s15, s20, s83
	s_add_i32 s15, s16, s15
	s_add_i32 s15, s15, 1
	s_mul_i32 s15, s15, s33
	v_add_u32_e32 v68, s15, v172
	s_mul_i32 s15, s25, s83
	v_add_u32_e32 v161, s15, v176
	v_add_u32_e32 v76, s26, v161
	v_add_u32_e32 v250, v183, v76
	ds_read_b128 v[72:75], v76 offset:2816
	ds_read_b128 v[78:81], v76 offset:2832
	ds_read_u16 v250, v250 offset:2816
	v_ashrrev_i32_e32 v69, 31, v68
	v_lshlrev_b64 v[68:69], 10, v[68:69]
	v_mov_b32_e32 v77, v137
	s_waitcnt lgkmcnt(1)
	v_lshlrev_b32_sdwa v76, v188, v72 dst_sel:DWORD dst_unused:UNUSED_PAD src0_sel:DWORD src1_sel:WORD_1
	v_lshlrev_b32_sdwa v136, v188, v72 dst_sel:DWORD dst_unused:UNUSED_PAD src0_sel:DWORD src1_sel:WORD_0
	v_lshl_add_u64 v[68:69], v[138:139], 0, v[68:69]
	v_lshl_add_u64 v[82:83], v[152:153], 0, v[136:137]
	v_lshl_add_u64 v[76:77], v[152:153], 0, v[76:77]
	v_lshlrev_b32_sdwa v72, v188, v73 dst_sel:DWORD dst_unused:UNUSED_PAD src0_sel:DWORD src1_sel:WORD_1
	v_lshlrev_b32_sdwa v136, v188, v73 dst_sel:DWORD dst_unused:UNUSED_PAD src0_sel:DWORD src1_sel:WORD_0
	v_mov_b32_e32 v73, v137
	global_load_dwordx4 v[68:71], v[68:69], off
	s_nop 0
	global_load_dwordx4 v[132:135], v[82:83], off
	global_load_dwordx4 v[124:127], v[76:77], off
	v_lshl_add_u64 v[76:77], v[152:153], 0, v[136:137]
	v_lshl_add_u64 v[72:73], v[152:153], 0, v[72:73]
	global_load_dwordx4 v[128:131], v[76:77], off
	global_load_dwordx4 v[116:119], v[72:73], off
	v_lshlrev_b32_sdwa v72, v188, v74 dst_sel:DWORD dst_unused:UNUSED_PAD src0_sel:DWORD src1_sel:WORD_1
	v_lshlrev_b32_sdwa v136, v188, v74 dst_sel:DWORD dst_unused:UNUSED_PAD src0_sel:DWORD src1_sel:WORD_0
	v_mov_b32_e32 v73, v137
	v_lshl_add_u64 v[76:77], v[152:153], 0, v[136:137]
	v_lshl_add_u64 v[72:73], v[152:153], 0, v[72:73]
	global_load_dwordx4 v[120:123], v[76:77], off
	global_load_dwordx4 v[108:111], v[72:73], off
	v_lshlrev_b32_sdwa v72, v188, v75 dst_sel:DWORD dst_unused:UNUSED_PAD src0_sel:DWORD src1_sel:WORD_1
	v_lshlrev_b32_sdwa v136, v188, v75 dst_sel:DWORD dst_unused:UNUSED_PAD src0_sel:DWORD src1_sel:WORD_0
	v_mov_b32_e32 v73, v137
	v_lshl_add_u64 v[74:75], v[152:153], 0, v[136:137]
	v_lshl_add_u64 v[72:73], v[152:153], 0, v[72:73]
	global_load_dwordx4 v[112:115], v[74:75], off
	global_load_dwordx4 v[100:103], v[72:73], off
	s_waitcnt lgkmcnt(0)
	v_lshlrev_b32_sdwa v72, v188, v78 dst_sel:DWORD dst_unused:UNUSED_PAD src0_sel:DWORD src1_sel:WORD_1
	v_lshlrev_b32_sdwa v136, v188, v78 dst_sel:DWORD dst_unused:UNUSED_PAD src0_sel:DWORD src1_sel:WORD_0
	v_mov_b32_e32 v73, v137
	v_lshl_add_u64 v[74:75], v[152:153], 0, v[136:137]
	v_lshl_add_u64 v[72:73], v[152:153], 0, v[72:73]
	global_load_dwordx4 v[104:107], v[74:75], off
	global_load_dwordx4 v[92:95], v[72:73], off
	v_lshlrev_b32_sdwa v72, v188, v79 dst_sel:DWORD dst_unused:UNUSED_PAD src0_sel:DWORD src1_sel:WORD_1
	v_lshlrev_b32_sdwa v136, v188, v79 dst_sel:DWORD dst_unused:UNUSED_PAD src0_sel:DWORD src1_sel:WORD_0
	v_mov_b32_e32 v73, v137
	v_lshl_add_u64 v[74:75], v[152:153], 0, v[136:137]
	v_lshl_add_u64 v[72:73], v[152:153], 0, v[72:73]
	global_load_dwordx4 v[96:99], v[74:75], off
	global_load_dwordx4 v[84:87], v[72:73], off
	v_lshlrev_b32_sdwa v72, v188, v80 dst_sel:DWORD dst_unused:UNUSED_PAD src0_sel:DWORD src1_sel:WORD_1
	v_lshlrev_b32_sdwa v136, v188, v80 dst_sel:DWORD dst_unused:UNUSED_PAD src0_sel:DWORD src1_sel:WORD_0
	v_mov_b32_e32 v73, v137
	v_lshl_add_u64 v[74:75], v[152:153], 0, v[136:137]
	v_lshl_add_u64 v[72:73], v[152:153], 0, v[72:73]
	global_load_dwordx4 v[88:91], v[74:75], off
	global_load_dwordx4 v[76:79], v[72:73], off
	v_lshlrev_b32_sdwa v72, v188, v81 dst_sel:DWORD dst_unused:UNUSED_PAD src0_sel:DWORD src1_sel:WORD_1
	v_lshlrev_b32_sdwa v136, v188, v81 dst_sel:DWORD dst_unused:UNUSED_PAD src0_sel:DWORD src1_sel:WORD_0
	v_mov_b32_e32 v73, v137
	v_lshl_add_u64 v[74:75], v[152:153], 0, v[136:137]
	v_lshl_add_u64 v[72:73], v[152:153], 0, v[72:73]
	global_load_dwordx4 v[80:83], v[74:75], off
	s_nop 0
	global_load_dwordx4 v[72:75], v[72:73], off
	v_lshlrev_b32_e32 v250, 2, v250
	global_load_dword v247, v250, s[40:41]
	global_load_dword v248, v250, s[36:37]
	global_load_dword v249, v250, s[38:39]
	s_mul_i32 s15, s20, s9
	s_mul_i32 s14, s81, s14
	v_mov_b32_e32 v136, v137
	v_mov_b32_e32 v163, v137
	s_waitcnt vmcnt(20)
	v_dot8c_i32_i4_e32 v136, v0, v16
	v_dot8c_i32_i4_e32 v163, v0, v12
	v_dot8c_i32_i4_e32 v136, v1, v17
	v_dot8c_i32_i4_e32 v163, v1, v13
	v_dot8c_i32_i4_e32 v136, v2, v18
	v_dot8c_i32_i4_e32 v163, v2, v14
	v_dot8c_i32_i4_e32 v136, v3, v19
	v_dot8c_i32_i4_e32 v163, v3, v15
	s_add_i32 s15, s16, s15
	s_add_i32 s17, s9, 1
	s_add_i32 s14, s16, s14
	ds_write2st64_b32 v180, v136, v163 offset0:34 offset1:35
	v_mov_b32_e32 v136, v137
	v_mov_b32_e32 v163, v137
	v_dot8c_i32_i4_e32 v136, v0, v8
	v_dot8c_i32_i4_e32 v163, v0, v4
	v_dot8c_i32_i4_e32 v136, v1, v9
	v_dot8c_i32_i4_e32 v163, v1, v5
	v_dot8c_i32_i4_e32 v136, v2, v10
	v_dot8c_i32_i4_e32 v163, v2, v6
	v_dot8c_i32_i4_e32 v136, v3, v11
	v_dot8c_i32_i4_e32 v163, v3, v7
	s_cmp_ge_u32 s15, s81
	s_cselect_b32 s17, s17, s9
	s_cselect_b32 s14, s14, s15
	ds_write2st64_b32 v180, v136, v163 offset0:36 offset1:37
	v_mov_b32_e32 v136, v137
	v_mov_b32_e32 v163, v137
	v_dot8c_i32_i4_e32 v136, v0, v20
	v_dot8c_i32_i4_e32 v163, v0, v24
	v_dot8c_i32_i4_e32 v136, v1, v21
	v_dot8c_i32_i4_e32 v163, v1, v25
	v_dot8c_i32_i4_e32 v136, v2, v22
	v_dot8c_i32_i4_e32 v163, v2, v26
	v_dot8c_i32_i4_e32 v136, v3, v23
	v_dot8c_i32_i4_e32 v163, v3, v27
	s_add_i32 s15, s17, 1
	s_cmp_ge_u32 s14, s81
	s_cselect_b32 s17, s15, s17
	ds_write2st64_b32 v180, v136, v163 offset0:38 offset1:39
	v_mov_b32_e32 v136, v137
	v_mov_b32_e32 v163, v137
	v_dot8c_i32_i4_e32 v136, v0, v28
	v_dot8c_i32_i4_e32 v163, v0, v32
	v_dot8c_i32_i4_e32 v136, v1, v29
	v_dot8c_i32_i4_e32 v163, v1, v33
	v_dot8c_i32_i4_e32 v136, v2, v30
	v_dot8c_i32_i4_e32 v163, v2, v34
	v_dot8c_i32_i4_e32 v136, v3, v31
	v_dot8c_i32_i4_e32 v163, v3, v35
	s_mul_i32 s14, s25, s17
	s_nop 1
	ds_write2st64_b32 v180, v136, v163 offset0:40 offset1:41
	v_mov_b32_e32 v136, v137
	v_mov_b32_e32 v163, v137
	v_dot8c_i32_i4_e32 v136, v0, v36
	v_dot8c_i32_i4_e32 v163, v0, v40
	v_dot8c_i32_i4_e32 v136, v1, v37
	v_dot8c_i32_i4_e32 v163, v1, v41
	v_dot8c_i32_i4_e32 v136, v2, v38
	v_dot8c_i32_i4_e32 v163, v2, v42
	v_dot8c_i32_i4_e32 v136, v3, v39
	v_dot8c_i32_i4_e32 v163, v3, v43
	s_nop 2
	ds_write2st64_b32 v180, v136, v163 offset0:42 offset1:43
	v_mov_b32_e32 v136, v137
	v_mov_b32_e32 v163, v137
	v_dot8c_i32_i4_e32 v136, v0, v44
	v_dot8c_i32_i4_e32 v163, v0, v48
	v_dot8c_i32_i4_e32 v136, v1, v45
	v_dot8c_i32_i4_e32 v163, v1, v49
	v_dot8c_i32_i4_e32 v136, v2, v46
	v_dot8c_i32_i4_e32 v163, v2, v50
	v_dot8c_i32_i4_e32 v136, v3, v47
	v_dot8c_i32_i4_e32 v163, v3, v51
	s_nop 2
	ds_write2st64_b32 v180, v136, v163 offset0:44 offset1:45
	v_mov_b32_e32 v136, v137
	v_mov_b32_e32 v163, v137
	v_dot8c_i32_i4_e32 v136, v0, v52
	v_dot8c_i32_i4_e32 v163, v0, v56
	v_dot8c_i32_i4_e32 v136, v1, v53
	v_dot8c_i32_i4_e32 v163, v1, v57
	v_dot8c_i32_i4_e32 v136, v2, v54
	v_dot8c_i32_i4_e32 v163, v2, v58
	v_dot8c_i32_i4_e32 v136, v3, v55
	v_dot8c_i32_i4_e32 v163, v3, v59
	s_nop 2
	ds_write2st64_b32 v180, v136, v163 offset0:46 offset1:47
	v_mov_b32_e32 v136, v137
	v_mov_b32_e32 v163, v137
	v_dot8c_i32_i4_e32 v136, v0, v60
	v_dot8c_i32_i4_e32 v163, v0, v64
	v_dot8c_i32_i4_e32 v136, v1, v61
	v_dot8c_i32_i4_e32 v163, v1, v65
	v_dot8c_i32_i4_e32 v136, v2, v62
	v_dot8c_i32_i4_e32 v163, v2, v66
	v_dot8c_i32_i4_e32 v136, v3, v63
	v_dot8c_i32_i4_e32 v163, v3, v67
	s_nop 2
	ds_write2st64_b32 v180, v136, v163 offset0:48 offset1:49
	s_waitcnt lgkmcnt(0)
	s_mul_i32 s14, s82, s17
	s_add_i32 s14, s19, s14
	v_add_u32_e32 v169, s14, v176
	ds_read_b128 v[194:197], v189 offset:8704
	ds_read_b128 v[198:201], v189 offset:8720
	ds_read_b128 v[202:205], v189 offset:8736
	ds_read_b128 v[206:209], v189 offset:8752
	s_waitcnt lgkmcnt(3)
	v_add_u32_e32 v167, v195, v194
	v_add3_u32 v167, v167, v196, v197
	s_waitcnt lgkmcnt(2)
	v_add3_u32 v167, v167, v199, v198
	v_add3_u32 v167, v167, v200, v201
	s_waitcnt lgkmcnt(1)
	v_add3_u32 v167, v167, v203, v202
	v_add3_u32 v167, v167, v204, v205
	s_waitcnt lgkmcnt(0)
	v_add3_u32 v167, v167, v207, v206
	v_add3_u32 v167, v167, v208, v209
	ds_read_b64 v[194:195], v169 offset:2304
	s_waitcnt lgkmcnt(0)
	v_mov_b32_e32 v196, v195
	v_add_u32_dpp v167, v167, v167 quad_perm:[1,0,3,2] row_mask:0xf bank_mask:0xf bound_ctrl:1
	v_cvt_f32_i32_e32 v197, v244
	v_add_u32_dpp v167, v167, v167 quad_perm:[2,3,0,1] row_mask:0xf bank_mask:0xf bound_ctrl:1
	v_cvt_f32_i32_e32 v163, v167
	v_pk_mul_f32 v[196:197], v[196:197], 0.5 op_sel_hi:[1,0]
	s_nop 0
	v_add_f32_e32 v163, v197, v163
	v_add_f32_e32 v163, v196, v163
	v_add_f32_e32 v163, 0x44000000, v163
	v_mul_f32_e32 v163, v194, v163
	v_mul_f32_e32 v163, v245, v163
	v_mul_f32_e32 v165, 0x3f3504f3, v163
	v_cmp_nlt_f32_e64 s[14:15], |v165|, 1.0
	s_and_saveexec_b64 s[84:85], s[14:15]
	s_xor_b64 s[14:15], exec, s[84:85]
	s_cbranch_execz .LBB0_792
	v_fma_f32 v167, |v165|, s66, v191
	v_fma_f32 v167, |v165|, v167, s67
	v_fma_f32 v167, |v165|, v167, s68
	v_fma_f32 v167, |v165|, v167, s69
	v_fma_f32 v167, |v165|, v167, s70
	v_fma_f32 v167, |v165|, v167, s71
	v_fma_f32 v167, |v165|, v167, |v165|
	v_mul_f32_e32 v169, 0xbfb8aa3b, v167
	v_fma_f32 v171, v167, s74, -v169
	v_rndne_f32_e32 v173, v169
	v_fmac_f32_e32 v171, 0xb2a5705f, v167
	v_sub_f32_e32 v169, v169, v173
	v_add_f32_e32 v169, v169, v171
	v_cvt_i32_f32_e32 v171, v173
	v_exp_f32_e32 v169, v169
	v_cmp_nlt_f32_e32 vcc, s75, v167
	v_ldexp_f32 v169, v169, v171
	s_nop 0
	v_cndmask_b32_e32 v169, 0, v169, vcc
	v_cmp_ngt_f32_e32 vcc, s76, v167
	s_nop 1
	v_cndmask_b32_e32 v167, v192, v169, vcc
	v_sub_f32_e32 v167, 1.0, v167
